# short gated conv fused into in-projection GEMM epilogue (DPP row shifts, halo rows fixed up in scan phase)
# speedup vs baseline: 1.0565x; 1.0460x over previous
; __device__ void phase_scan_sc(KP P, int layer) {
;     ...
;     bf16_t* proj = (bf16_t*)(P->ws + OFF_PROJ); const float* w = P->sc_w + layer * 3 * 1024;
;     for (int task = gtid; task < 2048 * 128; task += gthreads) {
;         const int ch = (task & 127) * 8; const long rowS = (long)(task >> 7) * 16; const int tin = (int)(rowS & (SEQ - 1));
;         float w0[8], w1[8], w2[8], hm2[8], hm1[8];
; #pragma unroll
;         for (int j = 0; j < 8; ++j) { w0[j] = w[ch + j]; w1[j] = w[1024 + ch + j]; w2[j] = w[2048 + ch + j]; hm2[j] = 0.f; hm1[j] = 0.f; }
;         if (tin >= 2) { unpack8(*(const u32x4*)(proj + (rowS - 2) * PW + COL_HC + ch), hm2); unpack8(*(const u32x4*)(proj + (rowS - 1) * PW + COL_HC + ch), hm1); }
; #pragma unroll
;         for (int i = 0; i < 16; ++i) { float h0[8], bz[8]; bf16_t* bp = proj + (rowS + i) * PW + COL_BZ + ch;
;             unpack8(__builtin_nontemporal_load((const u32x4*)(proj + (rowS + i) * PW + COL_HC + ch)), h0); unpack8(__builtin_nontemporal_load((const u32x4*)bp), bz);
;             float y[8];
; #pragma unroll
;             for (int j = 0; j < 8; ++j) { y[j] = bz[j] * (w0[j] * hm2[j] + w1[j] * hm1[j] + w2[j] * h0[j]); hm2[j] = hm1[j]; hm1[j] = h0[j]; }
;             *(u32x4*)bp = __builtin_bit_cast(u32x4, pack8(y)); }
;     }
.LBB0_64:
	s_or_b64 exec, exec, s[6:7]
	s_load_dwordx2 s[10:11], s[36:37], 0x58
	v_lshl_add_u32 v0, s2, 9, v208
	s_lshl_b32 s4, s54, 9
	s_mul_i32 s12, s94, 0x3000
	s_add_u32 s8, s90, 0x8d09200
	s_addc_u32 s9, s91, 0
	s_movk_i32 s1, 0x2200
	s_waitcnt lgkmcnt(0)
	s_add_u32 s10, s10, s12
	s_addc_u32 s11, s11, 0
	s_add_u32 s14, s10, 0x1000
	s_addc_u32 s15, s11, 0
	s_add_u32 s16, s10, 0x2000
	s_addc_u32 s17, s11, 0
	s_mov_b32 s3, 0x10000
	s_mov_b32 s13, 0xffff0000
	s_mov_b64 s[6:7], exec
	v_cmp_gt_u32_e32 vcc, s3, v0
	s_and_b64 exec, exec, vcc
	s_cbranch_execz .LBB0_69
.Lfix_loop:
	v_and_b32_e32 v1, 0x7f, v0
	v_lshrrev_b32_e32 v2, 7, v0
	v_lshlrev_b32_e32 v3, 6, v2
	v_lshlrev_b32_e32 v4, 5, v1
	v_lshlrev_b32_e32 v6, 4, v1
	v_mov_b32_e32 v7, 0
	v_lshl_add_u64 v[10:11], s[8:9], 0, v[6:7]
	v_mad_u64_u32 v[10:11], s[40:41], v3, s1, v[10:11]
	v_add_co_u32_e32 v12, vcc, 0x2200, v10
	s_nop 1
	v_addc_co_u32_e32 v13, vcc, 0, v11, vcc
	v_add_co_u32_e32 v14, vcc, 0xffffde00, v10
	s_nop 1
	v_addc_co_u32_e32 v15, vcc, -1, v11, vcc
	v_add_co_u32_e32 v16, vcc, 0xffffbc00, v10
	s_nop 1
	v_addc_co_u32_e32 v17, vcc, -1, v11, vcc
	global_load_dwordx4 v[20:23], v[16:17], off offset:2048
	global_load_dwordx4 v[24:27], v[14:15], off offset:2048
	global_load_dwordx4 v[28:31], v[10:11], off offset:2048
	global_load_dwordx4 v[32:35], v[12:13], off offset:2048
	global_load_dwordx4 v[36:39], v[10:11], off
	global_load_dwordx4 v[40:43], v[12:13], off
	global_load_dwordx4 v[44:47], v4, s[10:11]
	global_load_dwordx4 v[48:51], v4, s[10:11] offset:16
	global_load_dwordx4 v[52:55], v4, s[14:15]
	global_load_dwordx4 v[56:59], v4, s[14:15] offset:16
	global_load_dwordx4 v[60:63], v4, s[16:17]
	global_load_dwordx4 v[64:67], v4, s[16:17] offset:16
	v_and_b32_e32 v5, 0x1fff, v3
	v_cmp_eq_u32_e64 s[40:41], 0, v5
	s_waitcnt vmcnt(0)
	v_cndmask_b32_e64 v20, v20, 0, s[40:41]
	v_cndmask_b32_e64 v24, v24, 0, s[40:41]
	v_cndmask_b32_e64 v21, v21, 0, s[40:41]
	v_cndmask_b32_e64 v25, v25, 0, s[40:41]
	v_cndmask_b32_e64 v22, v22, 0, s[40:41]
	v_cndmask_b32_e64 v26, v26, 0, s[40:41]
	v_cndmask_b32_e64 v23, v23, 0, s[40:41]
	v_cndmask_b32_e64 v27, v27, 0, s[40:41]
	v_lshlrev_b32_e32 v68, 16, v20
	v_lshlrev_b32_e32 v69, 16, v24
	v_lshlrev_b32_e32 v70, 16, v28
	v_lshlrev_b32_e32 v71, 16, v32
	v_lshlrev_b32_e32 v72, 16, v36
	v_lshlrev_b32_e32 v73, 16, v40
	v_mul_f32_e32 v74, v44, v68
	v_mul_f32_e32 v75, v44, v69
	v_fmac_f32_e32 v74, v52, v69
	v_fmac_f32_e32 v75, v52, v70
	v_fmac_f32_e32 v74, v60, v70
	v_fmac_f32_e32 v75, v60, v71
	v_mul_f32_e32 v74, v72, v74
	v_mul_f32_e32 v75, v73, v75
	v_and_b32_e32 v76, s13, v20
	v_and_b32_e32 v77, s13, v24
	v_and_b32_e32 v78, s13, v28
	v_and_b32_e32 v79, s13, v32
	v_and_b32_e32 v80, s13, v36
	v_and_b32_e32 v81, s13, v40
	v_mul_f32_e32 v82, v45, v76
	v_mul_f32_e32 v83, v45, v77
	v_fmac_f32_e32 v82, v53, v77
	v_fmac_f32_e32 v83, v53, v78
	v_fmac_f32_e32 v82, v61, v78
	v_fmac_f32_e32 v83, v61, v79
	v_mul_f32_e32 v82, v80, v82
	v_mul_f32_e32 v83, v81, v83
	v_cvt_pk_bf16_f32 v84, v74, v82
	v_cvt_pk_bf16_f32 v88, v75, v83
	v_lshlrev_b32_e32 v68, 16, v21
	v_lshlrev_b32_e32 v69, 16, v25
	v_lshlrev_b32_e32 v70, 16, v29
	v_lshlrev_b32_e32 v71, 16, v33
	v_lshlrev_b32_e32 v72, 16, v37
	v_lshlrev_b32_e32 v73, 16, v41
	v_mul_f32_e32 v74, v46, v68
	v_mul_f32_e32 v75, v46, v69
	v_fmac_f32_e32 v74, v54, v69
	v_fmac_f32_e32 v75, v54, v70
	v_fmac_f32_e32 v74, v62, v70
	v_fmac_f32_e32 v75, v62, v71
	v_mul_f32_e32 v74, v72, v74
	v_mul_f32_e32 v75, v73, v75
	v_and_b32_e32 v76, s13, v21
	v_and_b32_e32 v77, s13, v25
	v_and_b32_e32 v78, s13, v29
	v_and_b32_e32 v79, s13, v33
	v_and_b32_e32 v80, s13, v37
	v_and_b32_e32 v81, s13, v41
	v_mul_f32_e32 v82, v47, v76
	v_mul_f32_e32 v83, v47, v77
	v_fmac_f32_e32 v82, v55, v77
	v_fmac_f32_e32 v83, v55, v78
	v_fmac_f32_e32 v82, v63, v78
	v_fmac_f32_e32 v83, v63, v79
	v_mul_f32_e32 v82, v80, v82
	v_mul_f32_e32 v83, v81, v83
	v_cvt_pk_bf16_f32 v85, v74, v82
	v_cvt_pk_bf16_f32 v89, v75, v83
	v_lshlrev_b32_e32 v68, 16, v22
	v_lshlrev_b32_e32 v69, 16, v26
	v_lshlrev_b32_e32 v70, 16, v30
	v_lshlrev_b32_e32 v71, 16, v34
	v_lshlrev_b32_e32 v72, 16, v38
	v_lshlrev_b32_e32 v73, 16, v42
	v_mul_f32_e32 v74, v48, v68
	v_mul_f32_e32 v75, v48, v69
	v_fmac_f32_e32 v74, v56, v69
	v_fmac_f32_e32 v75, v56, v70
	v_fmac_f32_e32 v74, v64, v70
	v_fmac_f32_e32 v75, v64, v71
	v_mul_f32_e32 v74, v72, v74
	v_mul_f32_e32 v75, v73, v75
	v_and_b32_e32 v76, s13, v22
	v_and_b32_e32 v77, s13, v26
	v_and_b32_e32 v78, s13, v30
	v_and_b32_e32 v79, s13, v34
	v_and_b32_e32 v80, s13, v38
	v_and_b32_e32 v81, s13, v42
	v_mul_f32_e32 v82, v49, v76
	v_mul_f32_e32 v83, v49, v77
	v_fmac_f32_e32 v82, v57, v77
	v_fmac_f32_e32 v83, v57, v78
	v_fmac_f32_e32 v82, v65, v78
	v_fmac_f32_e32 v83, v65, v79
	v_mul_f32_e32 v82, v80, v82
	v_mul_f32_e32 v83, v81, v83
	v_cvt_pk_bf16_f32 v86, v74, v82
	v_cvt_pk_bf16_f32 v90, v75, v83
	v_lshlrev_b32_e32 v68, 16, v23
	v_lshlrev_b32_e32 v69, 16, v27
	v_lshlrev_b32_e32 v70, 16, v31
	v_lshlrev_b32_e32 v71, 16, v35
	v_lshlrev_b32_e32 v72, 16, v39
	v_lshlrev_b32_e32 v73, 16, v43
	v_mul_f32_e32 v74, v50, v68
	v_mul_f32_e32 v75, v50, v69
	v_fmac_f32_e32 v74, v58, v69
	v_fmac_f32_e32 v75, v58, v70
	v_fmac_f32_e32 v74, v66, v70
	v_fmac_f32_e32 v75, v66, v71
	v_mul_f32_e32 v74, v72, v74
	v_mul_f32_e32 v75, v73, v75
	v_and_b32_e32 v76, s13, v23
	v_and_b32_e32 v77, s13, v27
	v_and_b32_e32 v78, s13, v31
	v_and_b32_e32 v79, s13, v35
	v_and_b32_e32 v80, s13, v39
	v_and_b32_e32 v81, s13, v43
	v_mul_f32_e32 v82, v51, v76
	v_mul_f32_e32 v83, v51, v77
	v_fmac_f32_e32 v82, v59, v77
	v_fmac_f32_e32 v83, v59, v78
	v_fmac_f32_e32 v82, v67, v78
	v_fmac_f32_e32 v83, v67, v79
	v_mul_f32_e32 v82, v80, v82
	v_mul_f32_e32 v83, v81, v83
	v_cvt_pk_bf16_f32 v87, v74, v82
	v_cvt_pk_bf16_f32 v91, v75, v83
	global_store_dwordx4 v[10:11], v[84:87], off
	global_store_dwordx4 v[12:13], v[88:91], off
	v_add_u32_e32 v0, s4, v0
	v_cmp_gt_u32_e32 vcc, s3, v0
	s_and_b64 exec, exec, vcc
	s_cbranch_execnz .Lfix_loop

; __device__ void phase_scan_sc(KP P, int layer) {
;     ...
;     bf16_t* proj = (bf16_t*)(P->ws + OFF_PROJ); const float* w = P->sc_w + layer * 3 * 1024;
;     for (int task = gtid; task < 2048 * 128; task += gthreads) {
;         const int ch = (task & 127) * 8; const long rowS = (long)(task >> 7) * 16; const int tin = (int)(rowS & (SEQ - 1));
;         float w0[8], w1[8], w2[8], hm2[8], hm1[8];
; #pragma unroll
;         for (int j = 0; j < 8; ++j) { w0[j] = w[ch + j]; w1[j] = w[1024 + ch + j]; w2[j] = w[2048 + ch + j]; hm2[j] = 0.f; hm1[j] = 0.f; }
.LBB0_105:
	s_cmp_lg_u32 s1, 0
	s_cbranch_scc1 .Lscw_skip
	s_load_dwordx2 s[16:17], s[36:37], 0x58
	s_andn2_b32 s18, 0x3000, s94
	v_mul_u32_u24_e32 v1, 24, v0
	s_waitcnt lgkmcnt(0)
	s_add_u32 s16, s16, s18
	s_addc_u32 s17, s17, 0
	global_load_dwordx2 v[2:3], v1, s[16:17]
	global_load_dwordx2 v[4:5], v1, s[16:17] offset:8
	global_load_dwordx2 v[6:7], v1, s[16:17] offset:16
	v_add_u32_e32 v1, 0x20800, v1
	s_waitcnt vmcnt(0)
	ds_write_b64 v1, v[2:3]
	ds_write_b64 v1, v[4:5] offset:8
	ds_write_b64 v1, v[6:7] offset:16

; #define LAS __attribute__((address_space(3)))
;     __device__ __forceinline__ void operator()(const f32x4 (&acc)[2][2][4][2], const Unit& u, int wr, int wc, int fr, int fq, const LAS float* rsl) const {
;         const int row0 = u.pm * 256 + wr * 64 + fr, pn = u.pn;
;         float rs[2][4];
; #pragma unroll
;         for (int ai = 0; ai < 2; ++ai)
; #pragma unroll
;             for (int m = 0; m < 4; ++m) rs[ai][m] = rsl[wr * 64 + fr + ai * 128 + m * 16];
; #pragma unroll
;         for (int ai = 0; ai < 2; ++ai)
; #pragma unroll
;             for (int m = 0; m < 4; ++m) {
;                 const int row = row0 + ai * 128 + m * 16;
;                 const float rstd = rsqrtf(rs[ai][m] * (1.f / 1024.f) + EPS);
;                 bf16_t* rp = proj + (size_t)row * PW + wc * 32 + 8 * fq;
;                 if (pn < 9) {
; #pragma unroll
;                     for (int bj = 0; bj < 2; ++bj) store8bf_nt(rp + pn * 256 + bj * 128, acc[ai][bj][m][0] * rstd, acc[ai][bj][m][1] * rstd);
;                 } else if (pn < 17) {
.LBB0_237:
	s_andn2_b64 vcc, exec, s[36:37]
	s_cbranch_vccnz .LBB0_108
	s_cmp_eq_u32 s1, 1
	s_mov_b64 s[36:37], -1
	s_cbranch_scc1 .LBB0_352
	v_lshl_add_u32 v128, s20, 2, v226
	ds_read2_b32 v[136:137], v128 offset1:16
	ds_read2_b32 v[134:135], v128 offset0:32 offset1:48
	ds_read2_b32 v[132:133], v128 offset0:128 offset1:144
	ds_read2_b32 v[130:131], v128 offset0:160 offset1:176
	s_add_i32 s35, s48, -9
	s_cmp_lt_u32 s35, 16
	s_cbranch_scc1 .Lepi_sc
	s_cmp_gt_i32 s48, 8
	s_waitcnt lgkmcnt(0)
	v_fmamk_f32 v129, v136, 0x3a800000, v209
	v_mul_f32_e32 v136, 0x4b800000, v129
	v_cmp_gt_f32_e32 vcc, s81, v129
	v_add_u32_e32 v128, s34, v171
	s_cselect_b64 s[44:45], -1, 0
	v_cndmask_b32_e32 v129, v129, v136, vcc
	v_rsq_f32_e32 v129, v129
	s_cmp_gt_u32 s48, 16
	s_cselect_b64 s[70:71], -1, 0
	s_cmp_gt_u32 s48, 24
	v_mul_f32_e32 v136, 0x45800000, v129
	v_mad_i64_i32 v[138:139], s[46:47], v128, s0, v[182:183]
	s_cselect_b64 s[36:37], -1, 0
	s_lshl_b32 s35, s48, 7
	v_cndmask_b32_e32 v136, v129, v136, vcc
	v_ashrrev_i32_e32 v129, 31, v128
	s_mov_b64 s[46:47], -1
	s_and_b64 vcc, exec, s[44:45]
	s_cbranch_vccz .LBB0_251
	s_and_b64 vcc, exec, s[70:71]
	s_cbranch_vccz .LBB0_248
	s_and_b64 vcc, exec, s[36:37]
	s_cbranch_vccz .LBB0_245
	s_and_saveexec_b64 s[46:47], s[26:27]
	s_cbranch_execz .LBB0_244
	v_lshlrev_b64 v[140:141], 6, v[128:129]
	v_lshl_add_u64 v[148:149], v[184:185], 0, v[140:141]
	v_pk_mul_f32 v[146:147], v[126:127], v[136:137] op_sel_hi:[1,0]
	v_pk_mul_f32 v[144:145], v[124:125], v[136:137] op_sel_hi:[1,0]
	v_pk_mul_f32 v[142:143], v[122:123], v[136:137] op_sel_hi:[1,0]
	v_pk_mul_f32 v[140:141], v[120:121], v[136:137] op_sel_hi:[1,0]
	global_store_dwordx4 v[148:149], v[144:147], off
	global_store_dwordx4 v[148:149], v[140:143], off offset:16

;     __device__ __forceinline__ void operator()(const f32x4 (&acc)[2][2][4][2], const Unit& u, int wr, int wc, int fr, int fq, const LAS float* rsl) const {
;     ...
;                 } else if (pn < 17) {
;                     f32x4 b0 = acc[ai][0][m][0] * rstd, b1 = acc[ai][0][m][1] * rstd, z0 = acc[ai][1][m][0] * rstd, z1 = acc[ai][1][m][1] * rstd;
; #pragma unroll
;                     for (int j = 0; j < 4; ++j) { float sa, sb; sigmoid2(z0[j], z1[j], sa, sb); b0[j] *= z0[j] * sa; b1[j] *= z1[j] * sb; }
;                     store8bf_nt(rp + COL_BZ + (pn - 9) * 128, b0, b1);
;                 } else if (pn < 25) {
;                     const float r2 = rstd * rstd;
;                     store8bf_nt(rp + COL_HC + (pn - 17) * 128, acc[ai][0][m][0] * acc[ai][1][m][0] * r2, acc[ai][0][m][1] * acc[ai][1][m][1] * r2);
; __device__ void phase_scan_sc(KP P, int layer) {
;     ...
;         float w0[8], w1[8], w2[8], hm2[8], hm1[8];
; #pragma unroll
;         for (int j = 0; j < 8; ++j) { w0[j] = w[ch + j]; w1[j] = w[1024 + ch + j]; w2[j] = w[2048 + ch + j]; hm2[j] = 0.f; hm1[j] = 0.f; }
;         if (tin >= 2) { unpack8(*(const u32x4*)(proj + (rowS - 2) * PW + COL_HC + ch), hm2); unpack8(*(const u32x4*)(proj + (rowS - 1) * PW + COL_HC + ch), hm1); }
; #pragma unroll
;         for (int i = 0; i < 16; ++i) { float h0[8], bz[8]; bf16_t* bp = proj + (rowS + i) * PW + COL_BZ + ch;
;             unpack8(__builtin_nontemporal_load((const u32x4*)(proj + (rowS + i) * PW + COL_HC + ch)), h0); unpack8(__builtin_nontemporal_load((const u32x4*)bp), bz);
;             float y[8];
; #pragma unroll
;             for (int j = 0; j < 8; ++j) { y[j] = bz[j] * (w0[j] * hm2[j] + w1[j] * hm1[j] + w2[j] * h0[j]); hm2[j] = hm1[j]; hm1[j] = h0[j]; }
;             *(u32x4*)bp = __builtin_bit_cast(u32x4, pack8(y)); }
.Lepi_sc:
	s_waitcnt lgkmcnt(0)
	v_add_u32_e32 v128, s34, v171
	s_lshl_b32 s44, s35, 7
	s_add_i32 s44, s44, 0x1200
	s_add_u32 s44, s98, s44
	s_addc_u32 s45, s99, 0
	v_mov_b32_e32 v206, v227
	v_mov_b32_e32 v207, 0
	v_lshl_add_u64 v[204:205], s[44:45], 0, v[206:207]
	v_mad_i64_i32 v[204:205], s[46:47], v128, s0, v[204:205]
	v_lshlrev_b32_e32 v206, 1, v227
	s_lshl_b32 s44, s35, 8
	s_add_i32 s44, s44, 0x20800
	v_add_u32_e32 v206, s44, v206
	ds_read_b128 v[138:141], v206
	ds_read_b128 v[142:145], v206 offset:4096
	ds_read_b128 v[146:149], v206 offset:8192
	v_and_b32_e32 v234, 15, v212
	v_cmp_gt_u32_e64 s[70:71], 2, v234
	v_cmp_lt_u32_e64 s[72:73], 13, v234
	v_fmamk_f32 v202, v136, 0x3a800000, v209
	v_rsq_f32_e32 v202, v202
	v_mul_f32_e32 v150, v124, v120
	v_mul_f32_e32 v151, v125, v121
	v_mul_f32_e32 v152, v126, v122
	v_mul_f32_e32 v153, v127, v123
	v_mul_f32_e32 v203, v202, v202
	v_mul_f32_e32 v150, v150, v203
	v_mul_f32_e32 v151, v151, v203
	v_mul_f32_e32 v152, v152, v203
	v_mul_f32_e32 v153, v153, v203
	v_mul_f32_e32 v158, v108, v202
	v_mul_f32_e32 v159, v109, v202
	v_mul_f32_e32 v160, v110, v202
	v_mul_f32_e32 v161, v111, v202
	v_min_f32_e64 v162, -v158, s52
	v_min_f32_e64 v163, -v159, s52
	v_min_f32_e64 v164, -v160, s52
	v_min_f32_e64 v165, -v161, s52
	v_mul_f32_e32 v162, 0x3fb8aa3b, v162
	v_mul_f32_e32 v163, 0x3fb8aa3b, v163
	v_mul_f32_e32 v164, 0x3fb8aa3b, v164
	v_mul_f32_e32 v165, 0x3fb8aa3b, v165
	v_exp_f32_e32 v162, v162
	v_exp_f32_e32 v163, v163
	v_exp_f32_e32 v164, v164
	v_exp_f32_e32 v165, v165
	s_nop 0
	v_add_f32_e32 v162, 1.0, v162
	v_add_f32_e32 v163, 1.0, v163
	v_add_f32_e32 v164, 1.0, v164
	v_add_f32_e32 v165, 1.0, v165
	v_mul_f32_e32 v166, v162, v163
	v_mul_f32_e32 v167, v164, v165
	v_rcp_f32_e32 v166, v166
	v_rcp_f32_e32 v167, v167
	s_nop 0
	v_mul_f32_e32 v206, v163, v166
	v_mul_f32_e32 v163, v162, v166
	v_mov_b32_e32 v162, v206
	v_mul_f32_e32 v206, v165, v167
	v_mul_f32_e32 v165, v164, v167
	v_mov_b32_e32 v164, v206
	v_mul_f32_e32 v158, v158, v162
	v_mul_f32_e32 v159, v159, v163
	v_mul_f32_e32 v160, v160, v164
	v_mul_f32_e32 v161, v161, v165
	v_mul_f32_e32 v162, v116, v202
	v_mul_f32_e32 v163, v117, v202
	v_mul_f32_e32 v164, v118, v202
	v_mul_f32_e32 v165, v119, v202
	v_mul_f32_e32 v158, v162, v158
	v_mul_f32_e32 v159, v163, v159
	v_mul_f32_e32 v160, v164, v160
	v_mul_f32_e32 v161, v165, v161
	v_mov_b32_e32 v194, 0
	v_mov_b32_e32 v198, 0
	v_mov_b32_e32 v195, 0
	v_mov_b32_e32 v199, 0
	v_mov_b32_e32 v196, 0
	v_mov_b32_e32 v200, 0
	v_mov_b32_e32 v197, 0
	v_mov_b32_e32 v201, 0
	s_nop 1
	v_mov_b32_dpp v194, v150 row_shr:1 row_mask:0xf bank_mask:0xf
	v_mov_b32_dpp v198, v150 row_shr:2 row_mask:0xf bank_mask:0xf
	v_mov_b32_dpp v195, v151 row_shr:1 row_mask:0xf bank_mask:0xf
	v_mov_b32_dpp v199, v151 row_shr:2 row_mask:0xf bank_mask:0xf
	v_mov_b32_dpp v196, v152 row_shr:1 row_mask:0xf bank_mask:0xf
	v_mov_b32_dpp v200, v152 row_shr:2 row_mask:0xf bank_mask:0xf
	v_mov_b32_dpp v197, v153 row_shr:1 row_mask:0xf bank_mask:0xf
	v_mov_b32_dpp v201, v153 row_shr:2 row_mask:0xf bank_mask:0xf
	s_waitcnt lgkmcnt(0)
	v_mul_f32_e32 v190, v138, v198
	v_mul_f32_e32 v191, v139, v199
	v_mul_f32_e32 v192, v140, v200
	v_mul_f32_e32 v193, v141, v201
	v_fmac_f32_e32 v190, v142, v194
	v_fmac_f32_e32 v191, v143, v195
	v_fmac_f32_e32 v192, v144, v196
	v_fmac_f32_e32 v193, v145, v197
	v_fmac_f32_e32 v190, v146, v150
	v_fmac_f32_e32 v191, v147, v151
	v_fmac_f32_e32 v192, v148, v152
	v_fmac_f32_e32 v193, v149, v153
	v_mul_f32_e32 v190, v158, v190
	v_mul_f32_e32 v191, v159, v191
	v_mul_f32_e32 v192, v160, v192
	v_mul_f32_e32 v193, v161, v193
	v_cndmask_b32_e64 v190, v190, v158, s[70:71]
	v_cndmask_b32_e64 v191, v191, v159, s[70:71]
	v_cndmask_b32_e64 v192, v192, v160, s[70:71]
	v_cndmask_b32_e64 v193, v193, v161, s[70:71]
	v_cvt_pk_bf16_f32 v230, v190, v191
	v_cvt_pk_bf16_f32 v231, v192, v193
	global_store_dwordx2 v[204:205], v[230:231], off
	v_cvt_pk_bf16_f32 v232, v150, v151
	v_cvt_pk_bf16_f32 v233, v152, v153
	s_mov_b64 exec, s[70:71]
	global_store_dwordx2 v[204:205], v[232:233], off offset:2048
	s_mov_b64 exec, -1
	v_add_co_u32_e32 v204, vcc, 0x22000, v204
	s_nop 1
	v_addc_co_u32_e32 v205, vcc, 0, v205, vcc
	v_fmamk_f32 v202, v137, 0x3a800000, v209
	v_rsq_f32_e32 v202, v202
	v_mul_f32_e32 v154, v112, v104
	v_mul_f32_e32 v155, v113, v105
	v_mul_f32_e32 v156, v114, v106
	v_mul_f32_e32 v157, v115, v107
	v_mul_f32_e32 v203, v202, v202
	v_mul_f32_e32 v154, v154, v203
	v_mul_f32_e32 v155, v155, v203
	v_mul_f32_e32 v156, v156, v203
	v_mul_f32_e32 v157, v157, v203
	v_mul_f32_e32 v158, v92, v202
	v_mul_f32_e32 v159, v93, v202
	v_mul_f32_e32 v160, v94, v202
	v_mul_f32_e32 v161, v95, v202
	v_min_f32_e64 v162, -v158, s52
	v_min_f32_e64 v163, -v159, s52
	v_min_f32_e64 v164, -v160, s52
	v_min_f32_e64 v165, -v161, s52
	v_mul_f32_e32 v162, 0x3fb8aa3b, v162
	v_mul_f32_e32 v163, 0x3fb8aa3b, v163
	v_mul_f32_e32 v164, 0x3fb8aa3b, v164
	v_mul_f32_e32 v165, 0x3fb8aa3b, v165
	v_exp_f32_e32 v162, v162
	v_exp_f32_e32 v163, v163
	v_exp_f32_e32 v164, v164
	v_exp_f32_e32 v165, v165
	s_nop 0
	v_add_f32_e32 v162, 1.0, v162
	v_add_f32_e32 v163, 1.0, v163
	v_add_f32_e32 v164, 1.0, v164
	v_add_f32_e32 v165, 1.0, v165
	v_mul_f32_e32 v166, v162, v163
	v_mul_f32_e32 v167, v164, v165
	v_rcp_f32_e32 v166, v166
	v_rcp_f32_e32 v167, v167
	s_nop 0
	v_mul_f32_e32 v206, v163, v166
	v_mul_f32_e32 v163, v162, v166
	v_mov_b32_e32 v162, v206
	v_mul_f32_e32 v206, v165, v167
	v_mul_f32_e32 v165, v164, v167
	v_mov_b32_e32 v164, v206
	v_mul_f32_e32 v158, v158, v162
	v_mul_f32_e32 v159, v159, v163
	v_mul_f32_e32 v160, v160, v164
	v_mul_f32_e32 v161, v161, v165
	v_mul_f32_e32 v162, v100, v202
;     __device__ __forceinline__ void operator()(const f32x4 (&acc)[2][2][4][2], const Unit& u, int wr, int wc, int fr, int fq, const LAS float* rsl) const {
;     ...
;                 } else if (pn < 17) {
;                     f32x4 b0 = acc[ai][0][m][0] * rstd, b1 = acc[ai][0][m][1] * rstd, z0 = acc[ai][1][m][0] * rstd, z1 = acc[ai][1][m][1] * rstd;
; #pragma unroll
;                     for (int j = 0; j < 4; ++j) { float sa, sb; sigmoid2(z0[j], z1[j], sa, sb); b0[j] *= z0[j] * sa; b1[j] *= z1[j] * sb; }
;                     store8bf_nt(rp + COL_BZ + (pn - 9) * 128, b0, b1);
;                 } else if (pn < 25) {
;                     const float r2 = rstd * rstd;
;                     store8bf_nt(rp + COL_HC + (pn - 17) * 128, acc[ai][0][m][0] * acc[ai][1][m][0] * r2, acc[ai][0][m][1] * acc[ai][1][m][1] * r2);
; __device__ void phase_scan_sc(KP P, int layer) {
;     ...
;         float w0[8], w1[8], w2[8], hm2[8], hm1[8];
; #pragma unroll
;         for (int j = 0; j < 8; ++j) { w0[j] = w[ch + j]; w1[j] = w[1024 + ch + j]; w2[j] = w[2048 + ch + j]; hm2[j] = 0.f; hm1[j] = 0.f; }
;         if (tin >= 2) { unpack8(*(const u32x4*)(proj + (rowS - 2) * PW + COL_HC + ch), hm2); unpack8(*(const u32x4*)(proj + (rowS - 1) * PW + COL_HC + ch), hm1); }
; #pragma unroll
;         for (int i = 0; i < 16; ++i) { float h0[8], bz[8]; bf16_t* bp = proj + (rowS + i) * PW + COL_BZ + ch;
;             unpack8(__builtin_nontemporal_load((const u32x4*)(proj + (rowS + i) * PW + COL_HC + ch)), h0); unpack8(__builtin_nontemporal_load((const u32x4*)bp), bz);
;             float y[8];
; #pragma unroll
;             for (int j = 0; j < 8; ++j) { y[j] = bz[j] * (w0[j] * hm2[j] + w1[j] * hm1[j] + w2[j] * h0[j]); hm2[j] = hm1[j]; hm1[j] = h0[j]; }
;             *(u32x4*)bp = __builtin_bit_cast(u32x4, pack8(y)); }
	v_mul_f32_e32 v163, v101, v202
	v_mul_f32_e32 v164, v102, v202
	v_mul_f32_e32 v165, v103, v202
	v_mul_f32_e32 v158, v162, v158
	v_mul_f32_e32 v159, v163, v159
	v_mul_f32_e32 v160, v164, v160
	v_mul_f32_e32 v161, v165, v161
	v_mov_b32_dpp v194, v150 row_ror:1 row_mask:0xf bank_mask:0xf
	v_mov_b32_dpp v198, v150 row_ror:2 row_mask:0xf bank_mask:0xf
	v_mov_b32_dpp v195, v151 row_ror:1 row_mask:0xf bank_mask:0xf
	v_mov_b32_dpp v199, v151 row_ror:2 row_mask:0xf bank_mask:0xf
	v_mov_b32_dpp v196, v152 row_ror:1 row_mask:0xf bank_mask:0xf
	v_mov_b32_dpp v200, v152 row_ror:2 row_mask:0xf bank_mask:0xf
	v_mov_b32_dpp v197, v153 row_ror:1 row_mask:0xf bank_mask:0xf
	v_mov_b32_dpp v201, v153 row_ror:2 row_mask:0xf bank_mask:0xf
	s_nop 1
	v_mov_b32_dpp v194, v154 row_shr:1 row_mask:0xf bank_mask:0xf
	v_mov_b32_dpp v198, v154 row_shr:2 row_mask:0xf bank_mask:0xf
	v_mov_b32_dpp v195, v155 row_shr:1 row_mask:0xf bank_mask:0xf
	v_mov_b32_dpp v199, v155 row_shr:2 row_mask:0xf bank_mask:0xf
	v_mov_b32_dpp v196, v156 row_shr:1 row_mask:0xf bank_mask:0xf
	v_mov_b32_dpp v200, v156 row_shr:2 row_mask:0xf bank_mask:0xf
	v_mov_b32_dpp v197, v157 row_shr:1 row_mask:0xf bank_mask:0xf
	v_mov_b32_dpp v201, v157 row_shr:2 row_mask:0xf bank_mask:0xf
	v_mul_f32_e32 v190, v138, v198
	v_mul_f32_e32 v191, v139, v199
	v_mul_f32_e32 v192, v140, v200
	v_mul_f32_e32 v193, v141, v201
	v_fmac_f32_e32 v190, v142, v194
	v_fmac_f32_e32 v191, v143, v195
	v_fmac_f32_e32 v192, v144, v196
	v_fmac_f32_e32 v193, v145, v197
	v_fmac_f32_e32 v190, v146, v154
	v_fmac_f32_e32 v191, v147, v155
	v_fmac_f32_e32 v192, v148, v156
	v_fmac_f32_e32 v193, v149, v157
	v_mul_f32_e32 v190, v158, v190
	v_mul_f32_e32 v191, v159, v191
	v_mul_f32_e32 v192, v160, v192
	v_mul_f32_e32 v193, v161, v193
	v_cvt_pk_bf16_f32 v230, v190, v191
	v_cvt_pk_bf16_f32 v231, v192, v193
	global_store_dwordx2 v[204:205], v[230:231], off
	v_add_co_u32_e32 v204, vcc, 0x22000, v204
	s_nop 1
	v_addc_co_u32_e32 v205, vcc, 0, v205, vcc
	v_fmamk_f32 v202, v134, 0x3a800000, v209
	v_rsq_f32_e32 v202, v202
	v_mul_f32_e32 v150, v96, v88
	v_mul_f32_e32 v151, v97, v89
	v_mul_f32_e32 v152, v98, v90
	v_mul_f32_e32 v153, v99, v91
	v_mul_f32_e32 v203, v202, v202
	v_mul_f32_e32 v150, v150, v203
	v_mul_f32_e32 v151, v151, v203
	v_mul_f32_e32 v152, v152, v203
	v_mul_f32_e32 v153, v153, v203
	v_mul_f32_e32 v158, v76, v202
	v_mul_f32_e32 v159, v77, v202
	v_mul_f32_e32 v160, v78, v202
	v_mul_f32_e32 v161, v79, v202
	v_min_f32_e64 v162, -v158, s52
	v_min_f32_e64 v163, -v159, s52
	v_min_f32_e64 v164, -v160, s52
	v_min_f32_e64 v165, -v161, s52
	v_mul_f32_e32 v162, 0x3fb8aa3b, v162
	v_mul_f32_e32 v163, 0x3fb8aa3b, v163
	v_mul_f32_e32 v164, 0x3fb8aa3b, v164
	v_mul_f32_e32 v165, 0x3fb8aa3b, v165
	v_exp_f32_e32 v162, v162
	v_exp_f32_e32 v163, v163
	v_exp_f32_e32 v164, v164
	v_exp_f32_e32 v165, v165
	s_nop 0
	v_add_f32_e32 v162, 1.0, v162
	v_add_f32_e32 v163, 1.0, v163
	v_add_f32_e32 v164, 1.0, v164
	v_add_f32_e32 v165, 1.0, v165
	v_mul_f32_e32 v166, v162, v163
	v_mul_f32_e32 v167, v164, v165
	v_rcp_f32_e32 v166, v166
	v_rcp_f32_e32 v167, v167
	s_nop 0
	v_mul_f32_e32 v206, v163, v166
	v_mul_f32_e32 v163, v162, v166
	v_mov_b32_e32 v162, v206
	v_mul_f32_e32 v206, v165, v167
	v_mul_f32_e32 v165, v164, v167
	v_mov_b32_e32 v164, v206
	v_mul_f32_e32 v158, v158, v162
	v_mul_f32_e32 v159, v159, v163
	v_mul_f32_e32 v160, v160, v164
	v_mul_f32_e32 v161, v161, v165
	v_mul_f32_e32 v162, v84, v202
	v_mul_f32_e32 v163, v85, v202
	v_mul_f32_e32 v164, v86, v202
	v_mul_f32_e32 v165, v87, v202
	v_mul_f32_e32 v158, v162, v158
	v_mul_f32_e32 v159, v163, v159
	v_mul_f32_e32 v160, v164, v160
	v_mul_f32_e32 v161, v165, v161
	v_mov_b32_dpp v194, v154 row_ror:1 row_mask:0xf bank_mask:0xf
	v_mov_b32_dpp v198, v154 row_ror:2 row_mask:0xf bank_mask:0xf
	v_mov_b32_dpp v195, v155 row_ror:1 row_mask:0xf bank_mask:0xf
	v_mov_b32_dpp v199, v155 row_ror:2 row_mask:0xf bank_mask:0xf
	v_mov_b32_dpp v196, v156 row_ror:1 row_mask:0xf bank_mask:0xf
	v_mov_b32_dpp v200, v156 row_ror:2 row_mask:0xf bank_mask:0xf
	v_mov_b32_dpp v197, v157 row_ror:1 row_mask:0xf bank_mask:0xf
	v_mov_b32_dpp v201, v157 row_ror:2 row_mask:0xf bank_mask:0xf
	s_nop 1
	v_mov_b32_dpp v194, v150 row_shr:1 row_mask:0xf bank_mask:0xf
	v_mov_b32_dpp v198, v150 row_shr:2 row_mask:0xf bank_mask:0xf
	v_mov_b32_dpp v195, v151 row_shr:1 row_mask:0xf bank_mask:0xf
	v_mov_b32_dpp v199, v151 row_shr:2 row_mask:0xf bank_mask:0xf
	v_mov_b32_dpp v196, v152 row_shr:1 row_mask:0xf bank_mask:0xf
	v_mov_b32_dpp v200, v152 row_shr:2 row_mask:0xf bank_mask:0xf
	v_mov_b32_dpp v197, v153 row_shr:1 row_mask:0xf bank_mask:0xf
	v_mov_b32_dpp v201, v153 row_shr:2 row_mask:0xf bank_mask:0xf
	v_mul_f32_e32 v190, v138, v198
	v_mul_f32_e32 v191, v139, v199
	v_mul_f32_e32 v192, v140, v200
	v_mul_f32_e32 v193, v141, v201
	v_fmac_f32_e32 v190, v142, v194
	v_fmac_f32_e32 v191, v143, v195
	v_fmac_f32_e32 v192, v144, v196
	v_fmac_f32_e32 v193, v145, v197
	v_fmac_f32_e32 v190, v146, v150
	v_fmac_f32_e32 v191, v147, v151
	v_fmac_f32_e32 v192, v148, v152
	v_fmac_f32_e32 v193, v149, v153
	v_mul_f32_e32 v190, v158, v190
	v_mul_f32_e32 v191, v159, v191
	v_mul_f32_e32 v192, v160, v192
	v_mul_f32_e32 v193, v161, v193
	v_cvt_pk_bf16_f32 v230, v190, v191
	v_cvt_pk_bf16_f32 v231, v192, v193
	global_store_dwordx2 v[204:205], v[230:231], off
	v_add_co_u32_e32 v204, vcc, 0x22000, v204
	s_nop 1
	v_addc_co_u32_e32 v205, vcc, 0, v205, vcc
	v_fmamk_f32 v202, v135, 0x3a800000, v209
	v_rsq_f32_e32 v202, v202
	v_mul_f32_e32 v154, v80, v72
	v_mul_f32_e32 v155, v81, v73
	v_mul_f32_e32 v156, v82, v74
	v_mul_f32_e32 v157, v83, v75
	v_mul_f32_e32 v203, v202, v202
;     __device__ __forceinline__ void operator()(const f32x4 (&acc)[2][2][4][2], const Unit& u, int wr, int wc, int fr, int fq, const LAS float* rsl) const {
;     ...
;                 } else if (pn < 17) {
;                     f32x4 b0 = acc[ai][0][m][0] * rstd, b1 = acc[ai][0][m][1] * rstd, z0 = acc[ai][1][m][0] * rstd, z1 = acc[ai][1][m][1] * rstd;
; #pragma unroll
;                     for (int j = 0; j < 4; ++j) { float sa, sb; sigmoid2(z0[j], z1[j], sa, sb); b0[j] *= z0[j] * sa; b1[j] *= z1[j] * sb; }
;                     store8bf_nt(rp + COL_BZ + (pn - 9) * 128, b0, b1);
;                 } else if (pn < 25) {
;                     const float r2 = rstd * rstd;
;                     store8bf_nt(rp + COL_HC + (pn - 17) * 128, acc[ai][0][m][0] * acc[ai][1][m][0] * r2, acc[ai][0][m][1] * acc[ai][1][m][1] * r2);
; __device__ void phase_scan_sc(KP P, int layer) {
;     ...
;         float w0[8], w1[8], w2[8], hm2[8], hm1[8];
; #pragma unroll
;         for (int j = 0; j < 8; ++j) { w0[j] = w[ch + j]; w1[j] = w[1024 + ch + j]; w2[j] = w[2048 + ch + j]; hm2[j] = 0.f; hm1[j] = 0.f; }
;         if (tin >= 2) { unpack8(*(const u32x4*)(proj + (rowS - 2) * PW + COL_HC + ch), hm2); unpack8(*(const u32x4*)(proj + (rowS - 1) * PW + COL_HC + ch), hm1); }
; #pragma unroll
;         for (int i = 0; i < 16; ++i) { float h0[8], bz[8]; bf16_t* bp = proj + (rowS + i) * PW + COL_BZ + ch;
;             unpack8(__builtin_nontemporal_load((const u32x4*)(proj + (rowS + i) * PW + COL_HC + ch)), h0); unpack8(__builtin_nontemporal_load((const u32x4*)bp), bz);
;             float y[8];
; #pragma unroll
;             for (int j = 0; j < 8; ++j) { y[j] = bz[j] * (w0[j] * hm2[j] + w1[j] * hm1[j] + w2[j] * h0[j]); hm2[j] = hm1[j]; hm1[j] = h0[j]; }
;             *(u32x4*)bp = __builtin_bit_cast(u32x4, pack8(y)); }
	v_mul_f32_e32 v154, v154, v203
	v_mul_f32_e32 v155, v155, v203
	v_mul_f32_e32 v156, v156, v203
	v_mul_f32_e32 v157, v157, v203
	v_mul_f32_e32 v158, v64, v202
	v_mul_f32_e32 v159, v65, v202
	v_mul_f32_e32 v160, v66, v202
	v_mul_f32_e32 v161, v67, v202
	v_min_f32_e64 v162, -v158, s52
	v_min_f32_e64 v163, -v159, s52
	v_min_f32_e64 v164, -v160, s52
	v_min_f32_e64 v165, -v161, s52
	v_mul_f32_e32 v162, 0x3fb8aa3b, v162
	v_mul_f32_e32 v163, 0x3fb8aa3b, v163
	v_mul_f32_e32 v164, 0x3fb8aa3b, v164
	v_mul_f32_e32 v165, 0x3fb8aa3b, v165
	v_exp_f32_e32 v162, v162
	v_exp_f32_e32 v163, v163
	v_exp_f32_e32 v164, v164
	v_exp_f32_e32 v165, v165
	s_nop 0
	v_add_f32_e32 v162, 1.0, v162
	v_add_f32_e32 v163, 1.0, v163
	v_add_f32_e32 v164, 1.0, v164
	v_add_f32_e32 v165, 1.0, v165
	v_mul_f32_e32 v166, v162, v163
	v_mul_f32_e32 v167, v164, v165
	v_rcp_f32_e32 v166, v166
	v_rcp_f32_e32 v167, v167
	s_nop 0
	v_mul_f32_e32 v206, v163, v166
	v_mul_f32_e32 v163, v162, v166
	v_mov_b32_e32 v162, v206
	v_mul_f32_e32 v206, v165, v167
	v_mul_f32_e32 v165, v164, v167
	v_mov_b32_e32 v164, v206
	v_mul_f32_e32 v158, v158, v162
	v_mul_f32_e32 v159, v159, v163
	v_mul_f32_e32 v160, v160, v164
	v_mul_f32_e32 v161, v161, v165
	v_mul_f32_e32 v162, v68, v202
	v_mul_f32_e32 v163, v69, v202
	v_mul_f32_e32 v164, v70, v202
	v_mul_f32_e32 v165, v71, v202
	v_mul_f32_e32 v158, v162, v158
	v_mul_f32_e32 v159, v163, v159
	v_mul_f32_e32 v160, v164, v160
	v_mul_f32_e32 v161, v165, v161
	v_mov_b32_dpp v194, v150 row_ror:1 row_mask:0xf bank_mask:0xf
	v_mov_b32_dpp v198, v150 row_ror:2 row_mask:0xf bank_mask:0xf
	v_mov_b32_dpp v195, v151 row_ror:1 row_mask:0xf bank_mask:0xf
	v_mov_b32_dpp v199, v151 row_ror:2 row_mask:0xf bank_mask:0xf
	v_mov_b32_dpp v196, v152 row_ror:1 row_mask:0xf bank_mask:0xf
	v_mov_b32_dpp v200, v152 row_ror:2 row_mask:0xf bank_mask:0xf
	v_mov_b32_dpp v197, v153 row_ror:1 row_mask:0xf bank_mask:0xf
	v_mov_b32_dpp v201, v153 row_ror:2 row_mask:0xf bank_mask:0xf
	s_nop 1
	v_mov_b32_dpp v194, v154 row_shr:1 row_mask:0xf bank_mask:0xf
	v_mov_b32_dpp v198, v154 row_shr:2 row_mask:0xf bank_mask:0xf
	v_mov_b32_dpp v195, v155 row_shr:1 row_mask:0xf bank_mask:0xf
	v_mov_b32_dpp v199, v155 row_shr:2 row_mask:0xf bank_mask:0xf
	v_mov_b32_dpp v196, v156 row_shr:1 row_mask:0xf bank_mask:0xf
	v_mov_b32_dpp v200, v156 row_shr:2 row_mask:0xf bank_mask:0xf
	v_mov_b32_dpp v197, v157 row_shr:1 row_mask:0xf bank_mask:0xf
	v_mov_b32_dpp v201, v157 row_shr:2 row_mask:0xf bank_mask:0xf
	v_mul_f32_e32 v190, v138, v198
	v_mul_f32_e32 v191, v139, v199
	v_mul_f32_e32 v192, v140, v200
	v_mul_f32_e32 v193, v141, v201
	v_fmac_f32_e32 v190, v142, v194
	v_fmac_f32_e32 v191, v143, v195
	v_fmac_f32_e32 v192, v144, v196
	v_fmac_f32_e32 v193, v145, v197
	v_fmac_f32_e32 v190, v146, v154
	v_fmac_f32_e32 v191, v147, v155
	v_fmac_f32_e32 v192, v148, v156
	v_fmac_f32_e32 v193, v149, v157
	v_mul_f32_e32 v190, v158, v190
	v_mul_f32_e32 v191, v159, v191
	v_mul_f32_e32 v192, v160, v192
	v_mul_f32_e32 v193, v161, v193
	v_cvt_pk_bf16_f32 v230, v190, v191
	v_cvt_pk_bf16_f32 v231, v192, v193
	global_store_dwordx2 v[204:205], v[230:231], off
	v_cvt_pk_bf16_f32 v232, v154, v155
	v_cvt_pk_bf16_f32 v233, v156, v157
	s_mov_b64 exec, s[72:73]
	global_store_dwordx2 v[204:205], v[232:233], off offset:2048
	s_mov_b64 exec, -1
	v_add_co_u32_e32 v204, vcc, 0xaa000, v204
	s_nop 1
	v_addc_co_u32_e32 v205, vcc, 0, v205, vcc
	v_fmamk_f32 v202, v132, 0x3a800000, v209
	v_rsq_f32_e32 v202, v202
	v_mul_f32_e32 v150, v60, v56
	v_mul_f32_e32 v151, v61, v57
	v_mul_f32_e32 v152, v62, v58
	v_mul_f32_e32 v153, v63, v59
	v_mul_f32_e32 v203, v202, v202
	v_mul_f32_e32 v150, v150, v203
	v_mul_f32_e32 v151, v151, v203
	v_mul_f32_e32 v152, v152, v203
	v_mul_f32_e32 v153, v153, v203
	v_mul_f32_e32 v158, v40, v202
	v_mul_f32_e32 v159, v41, v202
	v_mul_f32_e32 v160, v42, v202
	v_mul_f32_e32 v161, v43, v202
	v_min_f32_e64 v162, -v158, s52
	v_min_f32_e64 v163, -v159, s52
	v_min_f32_e64 v164, -v160, s52
	v_min_f32_e64 v165, -v161, s52
	v_mul_f32_e32 v162, 0x3fb8aa3b, v162
	v_mul_f32_e32 v163, 0x3fb8aa3b, v163
	v_mul_f32_e32 v164, 0x3fb8aa3b, v164
	v_mul_f32_e32 v165, 0x3fb8aa3b, v165
	v_exp_f32_e32 v162, v162
	v_exp_f32_e32 v163, v163
	v_exp_f32_e32 v164, v164
	v_exp_f32_e32 v165, v165
	s_nop 0
	v_add_f32_e32 v162, 1.0, v162
	v_add_f32_e32 v163, 1.0, v163
	v_add_f32_e32 v164, 1.0, v164
	v_add_f32_e32 v165, 1.0, v165
	v_mul_f32_e32 v166, v162, v163
	v_mul_f32_e32 v167, v164, v165
	v_rcp_f32_e32 v166, v166
	v_rcp_f32_e32 v167, v167
	s_nop 0
	v_mul_f32_e32 v206, v163, v166
	v_mul_f32_e32 v163, v162, v166
	v_mov_b32_e32 v162, v206
	v_mul_f32_e32 v206, v165, v167
	v_mul_f32_e32 v165, v164, v167
	v_mov_b32_e32 v164, v206
	v_mul_f32_e32 v158, v158, v162
	v_mul_f32_e32 v159, v159, v163
	v_mul_f32_e32 v160, v160, v164
	v_mul_f32_e32 v161, v161, v165
	v_mul_f32_e32 v162, v48, v202
	v_mul_f32_e32 v163, v49, v202
	v_mul_f32_e32 v164, v50, v202
	v_mul_f32_e32 v165, v51, v202
	v_mul_f32_e32 v158, v162, v158
	v_mul_f32_e32 v159, v163, v159
	v_mul_f32_e32 v160, v164, v160
	v_mul_f32_e32 v161, v165, v161
	v_mov_b32_e32 v194, 0
	v_mov_b32_e32 v198, 0
	v_mov_b32_e32 v195, 0
	v_mov_b32_e32 v199, 0
	v_mov_b32_e32 v196, 0
	v_mov_b32_e32 v200, 0
	v_mov_b32_e32 v197, 0
	v_mov_b32_e32 v201, 0
	s_nop 1
	v_mov_b32_dpp v194, v150 row_shr:1 row_mask:0xf bank_mask:0xf
	v_mov_b32_dpp v198, v150 row_shr:2 row_mask:0xf bank_mask:0xf
	v_mov_b32_dpp v195, v151 row_shr:1 row_mask:0xf bank_mask:0xf
	v_mov_b32_dpp v199, v151 row_shr:2 row_mask:0xf bank_mask:0xf
	v_mov_b32_dpp v196, v152 row_shr:1 row_mask:0xf bank_mask:0xf
	v_mov_b32_dpp v200, v152 row_shr:2 row_mask:0xf bank_mask:0xf
;     __device__ __forceinline__ void operator()(const f32x4 (&acc)[2][2][4][2], const Unit& u, int wr, int wc, int fr, int fq, const LAS float* rsl) const {
;     ...
;                     f32x4 b0 = acc[ai][0][m][0] * rstd, b1 = acc[ai][0][m][1] * rstd, z0 = acc[ai][1][m][0] * rstd, z1 = acc[ai][1][m][1] * rstd;
; #pragma unroll
;                     for (int j = 0; j < 4; ++j) { float sa, sb; sigmoid2(z0[j], z1[j], sa, sb); b0[j] *= z0[j] * sa; b1[j] *= z1[j] * sb; }
;                     store8bf_nt(rp + COL_BZ + (pn - 9) * 128, b0, b1);
;                 } else if (pn < 25) {
;                     const float r2 = rstd * rstd;
;                     store8bf_nt(rp + COL_HC + (pn - 17) * 128, acc[ai][0][m][0] * acc[ai][1][m][0] * r2, acc[ai][0][m][1] * acc[ai][1][m][1] * r2);
; __device__ void phase_scan_sc(KP P, int layer) {
;     ...
;         for (int i = 0; i < 16; ++i) { float h0[8], bz[8]; bf16_t* bp = proj + (rowS + i) * PW + COL_BZ + ch;
;             unpack8(__builtin_nontemporal_load((const u32x4*)(proj + (rowS + i) * PW + COL_HC + ch)), h0); unpack8(__builtin_nontemporal_load((const u32x4*)bp), bz);
;             float y[8];
; #pragma unroll
;             for (int j = 0; j < 8; ++j) { y[j] = bz[j] * (w0[j] * hm2[j] + w1[j] * hm1[j] + w2[j] * h0[j]); hm2[j] = hm1[j]; hm1[j] = h0[j]; }
;             *(u32x4*)bp = __builtin_bit_cast(u32x4, pack8(y)); }
	v_mov_b32_dpp v197, v153 row_shr:1 row_mask:0xf bank_mask:0xf
	v_mov_b32_dpp v201, v153 row_shr:2 row_mask:0xf bank_mask:0xf
	v_mul_f32_e32 v190, v138, v198
	v_mul_f32_e32 v191, v139, v199
	v_mul_f32_e32 v192, v140, v200
	v_mul_f32_e32 v193, v141, v201
	v_fmac_f32_e32 v190, v142, v194
	v_fmac_f32_e32 v191, v143, v195
	v_fmac_f32_e32 v192, v144, v196
	v_fmac_f32_e32 v193, v145, v197
	v_fmac_f32_e32 v190, v146, v150
	v_fmac_f32_e32 v191, v147, v151
	v_fmac_f32_e32 v192, v148, v152
	v_fmac_f32_e32 v193, v149, v153
	v_mul_f32_e32 v190, v158, v190
	v_mul_f32_e32 v191, v159, v191
	v_mul_f32_e32 v192, v160, v192
	v_mul_f32_e32 v193, v161, v193
	v_cndmask_b32_e64 v190, v190, v158, s[70:71]
	v_cndmask_b32_e64 v191, v191, v159, s[70:71]
	v_cndmask_b32_e64 v192, v192, v160, s[70:71]
	v_cndmask_b32_e64 v193, v193, v161, s[70:71]
	v_cvt_pk_bf16_f32 v230, v190, v191
	v_cvt_pk_bf16_f32 v231, v192, v193
	global_store_dwordx2 v[204:205], v[230:231], off
	v_cvt_pk_bf16_f32 v232, v150, v151
	v_cvt_pk_bf16_f32 v233, v152, v153
	s_mov_b64 exec, s[70:71]
	global_store_dwordx2 v[204:205], v[232:233], off offset:2048
	s_mov_b64 exec, -1
	v_add_co_u32_e32 v204, vcc, 0x22000, v204
	s_nop 1
	v_addc_co_u32_e32 v205, vcc, 0, v205, vcc
	v_fmamk_f32 v202, v133, 0x3a800000, v209
	v_rsq_f32_e32 v202, v202
	v_mul_f32_e32 v154, v52, v44
	v_mul_f32_e32 v155, v53, v45
	v_mul_f32_e32 v156, v54, v46
	v_mul_f32_e32 v157, v55, v47
	v_mul_f32_e32 v203, v202, v202
	v_mul_f32_e32 v154, v154, v203
	v_mul_f32_e32 v155, v155, v203
	v_mul_f32_e32 v156, v156, v203
	v_mul_f32_e32 v157, v157, v203
	v_mul_f32_e32 v158, v24, v202
	v_mul_f32_e32 v159, v25, v202
	v_mul_f32_e32 v160, v26, v202
	v_mul_f32_e32 v161, v27, v202
	v_min_f32_e64 v162, -v158, s52
	v_min_f32_e64 v163, -v159, s52
	v_min_f32_e64 v164, -v160, s52
	v_min_f32_e64 v165, -v161, s52
	v_mul_f32_e32 v162, 0x3fb8aa3b, v162
	v_mul_f32_e32 v163, 0x3fb8aa3b, v163
	v_mul_f32_e32 v164, 0x3fb8aa3b, v164
	v_mul_f32_e32 v165, 0x3fb8aa3b, v165
	v_exp_f32_e32 v162, v162
	v_exp_f32_e32 v163, v163
	v_exp_f32_e32 v164, v164
	v_exp_f32_e32 v165, v165
	s_nop 0
	v_add_f32_e32 v162, 1.0, v162
	v_add_f32_e32 v163, 1.0, v163
	v_add_f32_e32 v164, 1.0, v164
	v_add_f32_e32 v165, 1.0, v165
	v_mul_f32_e32 v166, v162, v163
	v_mul_f32_e32 v167, v164, v165
	v_rcp_f32_e32 v166, v166
	v_rcp_f32_e32 v167, v167
	s_nop 0
	v_mul_f32_e32 v206, v163, v166
	v_mul_f32_e32 v163, v162, v166
	v_mov_b32_e32 v162, v206
	v_mul_f32_e32 v206, v165, v167
	v_mul_f32_e32 v165, v164, v167
	v_mov_b32_e32 v164, v206
	v_mul_f32_e32 v158, v158, v162
	v_mul_f32_e32 v159, v159, v163
	v_mul_f32_e32 v160, v160, v164
	v_mul_f32_e32 v161, v161, v165
	v_mul_f32_e32 v162, v32, v202
	v_mul_f32_e32 v163, v33, v202
	v_mul_f32_e32 v164, v34, v202
	v_mul_f32_e32 v165, v35, v202
	v_mul_f32_e32 v158, v162, v158
	v_mul_f32_e32 v159, v163, v159
	v_mul_f32_e32 v160, v164, v160
	v_mul_f32_e32 v161, v165, v161
	v_mov_b32_dpp v194, v150 row_ror:1 row_mask:0xf bank_mask:0xf
	v_mov_b32_dpp v198, v150 row_ror:2 row_mask:0xf bank_mask:0xf
	v_mov_b32_dpp v195, v151 row_ror:1 row_mask:0xf bank_mask:0xf
	v_mov_b32_dpp v199, v151 row_ror:2 row_mask:0xf bank_mask:0xf
	v_mov_b32_dpp v196, v152 row_ror:1 row_mask:0xf bank_mask:0xf
	v_mov_b32_dpp v200, v152 row_ror:2 row_mask:0xf bank_mask:0xf
	v_mov_b32_dpp v197, v153 row_ror:1 row_mask:0xf bank_mask:0xf
	v_mov_b32_dpp v201, v153 row_ror:2 row_mask:0xf bank_mask:0xf
	s_nop 1
	v_mov_b32_dpp v194, v154 row_shr:1 row_mask:0xf bank_mask:0xf
	v_mov_b32_dpp v198, v154 row_shr:2 row_mask:0xf bank_mask:0xf
	v_mov_b32_dpp v195, v155 row_shr:1 row_mask:0xf bank_mask:0xf
	v_mov_b32_dpp v199, v155 row_shr:2 row_mask:0xf bank_mask:0xf
	v_mov_b32_dpp v196, v156 row_shr:1 row_mask:0xf bank_mask:0xf
	v_mov_b32_dpp v200, v156 row_shr:2 row_mask:0xf bank_mask:0xf
	v_mov_b32_dpp v197, v157 row_shr:1 row_mask:0xf bank_mask:0xf
	v_mov_b32_dpp v201, v157 row_shr:2 row_mask:0xf bank_mask:0xf
	v_mul_f32_e32 v190, v138, v198
	v_mul_f32_e32 v191, v139, v199
	v_mul_f32_e32 v192, v140, v200
	v_mul_f32_e32 v193, v141, v201
	v_fmac_f32_e32 v190, v142, v194
	v_fmac_f32_e32 v191, v143, v195
	v_fmac_f32_e32 v192, v144, v196
	v_fmac_f32_e32 v193, v145, v197
	v_fmac_f32_e32 v190, v146, v154
	v_fmac_f32_e32 v191, v147, v155
	v_fmac_f32_e32 v192, v148, v156
	v_fmac_f32_e32 v193, v149, v157
	v_mul_f32_e32 v190, v158, v190
	v_mul_f32_e32 v191, v159, v191
	v_mul_f32_e32 v192, v160, v192
	v_mul_f32_e32 v193, v161, v193
	v_cvt_pk_bf16_f32 v230, v190, v191
	v_cvt_pk_bf16_f32 v231, v192, v193
	global_store_dwordx2 v[204:205], v[230:231], off
	v_add_co_u32_e32 v204, vcc, 0x22000, v204
	s_nop 1
	v_addc_co_u32_e32 v205, vcc, 0, v205, vcc
	v_fmamk_f32 v202, v130, 0x3a800000, v209
	v_rsq_f32_e32 v202, v202
	v_mul_f32_e32 v150, v36, v28
	v_mul_f32_e32 v151, v37, v29
	v_mul_f32_e32 v152, v38, v30
	v_mul_f32_e32 v153, v39, v31
	v_mul_f32_e32 v203, v202, v202
	v_mul_f32_e32 v150, v150, v203
	v_mul_f32_e32 v151, v151, v203
	v_mul_f32_e32 v152, v152, v203
	v_mul_f32_e32 v153, v153, v203
	v_mul_f32_e32 v158, v8, v202
	v_mul_f32_e32 v159, v9, v202
	v_mul_f32_e32 v160, v10, v202
	v_mul_f32_e32 v161, v11, v202
	v_min_f32_e64 v162, -v158, s52
	v_min_f32_e64 v163, -v159, s52
	v_min_f32_e64 v164, -v160, s52
	v_min_f32_e64 v165, -v161, s52
	v_mul_f32_e32 v162, 0x3fb8aa3b, v162
	v_mul_f32_e32 v163, 0x3fb8aa3b, v163
	v_mul_f32_e32 v164, 0x3fb8aa3b, v164
	v_mul_f32_e32 v165, 0x3fb8aa3b, v165
	v_exp_f32_e32 v162, v162
	v_exp_f32_e32 v163, v163
	v_exp_f32_e32 v164, v164
	v_exp_f32_e32 v165, v165
	s_nop 0
	v_add_f32_e32 v162, 1.0, v162
	v_add_f32_e32 v163, 1.0, v163
	v_add_f32_e32 v164, 1.0, v164
	v_add_f32_e32 v165, 1.0, v165
;     __device__ __forceinline__ void operator()(const f32x4 (&acc)[2][2][4][2], const Unit& u, int wr, int wc, int fr, int fq, const LAS float* rsl) const {
;     ...
;                     f32x4 b0 = acc[ai][0][m][0] * rstd, b1 = acc[ai][0][m][1] * rstd, z0 = acc[ai][1][m][0] * rstd, z1 = acc[ai][1][m][1] * rstd;
; #pragma unroll
;                     for (int j = 0; j < 4; ++j) { float sa, sb; sigmoid2(z0[j], z1[j], sa, sb); b0[j] *= z0[j] * sa; b1[j] *= z1[j] * sb; }
;                     store8bf_nt(rp + COL_BZ + (pn - 9) * 128, b0, b1);
;                 } else if (pn < 25) {
;                     const float r2 = rstd * rstd;
;                     store8bf_nt(rp + COL_HC + (pn - 17) * 128, acc[ai][0][m][0] * acc[ai][1][m][0] * r2, acc[ai][0][m][1] * acc[ai][1][m][1] * r2);
; __device__ void phase_scan_sc(KP P, int layer) {
;     ...
;         for (int i = 0; i < 16; ++i) { float h0[8], bz[8]; bf16_t* bp = proj + (rowS + i) * PW + COL_BZ + ch;
;             unpack8(__builtin_nontemporal_load((const u32x4*)(proj + (rowS + i) * PW + COL_HC + ch)), h0); unpack8(__builtin_nontemporal_load((const u32x4*)bp), bz);
;             float y[8];
; #pragma unroll
;             for (int j = 0; j < 8; ++j) { y[j] = bz[j] * (w0[j] * hm2[j] + w1[j] * hm1[j] + w2[j] * h0[j]); hm2[j] = hm1[j]; hm1[j] = h0[j]; }
;             *(u32x4*)bp = __builtin_bit_cast(u32x4, pack8(y)); }
	v_mul_f32_e32 v166, v162, v163
	v_mul_f32_e32 v167, v164, v165
	v_rcp_f32_e32 v166, v166
	v_rcp_f32_e32 v167, v167
	s_nop 0
	v_mul_f32_e32 v206, v163, v166
	v_mul_f32_e32 v163, v162, v166
	v_mov_b32_e32 v162, v206
	v_mul_f32_e32 v206, v165, v167
	v_mul_f32_e32 v165, v164, v167
	v_mov_b32_e32 v164, v206
	v_mul_f32_e32 v158, v158, v162
	v_mul_f32_e32 v159, v159, v163
	v_mul_f32_e32 v160, v160, v164
	v_mul_f32_e32 v161, v161, v165
	v_mul_f32_e32 v162, v16, v202
	v_mul_f32_e32 v163, v17, v202
	v_mul_f32_e32 v164, v18, v202
	v_mul_f32_e32 v165, v19, v202
	v_mul_f32_e32 v158, v162, v158
	v_mul_f32_e32 v159, v163, v159
	v_mul_f32_e32 v160, v164, v160
	v_mul_f32_e32 v161, v165, v161
	v_mov_b32_dpp v194, v154 row_ror:1 row_mask:0xf bank_mask:0xf
	v_mov_b32_dpp v198, v154 row_ror:2 row_mask:0xf bank_mask:0xf
	v_mov_b32_dpp v195, v155 row_ror:1 row_mask:0xf bank_mask:0xf
	v_mov_b32_dpp v199, v155 row_ror:2 row_mask:0xf bank_mask:0xf
	v_mov_b32_dpp v196, v156 row_ror:1 row_mask:0xf bank_mask:0xf
	v_mov_b32_dpp v200, v156 row_ror:2 row_mask:0xf bank_mask:0xf
	v_mov_b32_dpp v197, v157 row_ror:1 row_mask:0xf bank_mask:0xf
	v_mov_b32_dpp v201, v157 row_ror:2 row_mask:0xf bank_mask:0xf
	s_nop 1
	v_mov_b32_dpp v194, v150 row_shr:1 row_mask:0xf bank_mask:0xf
	v_mov_b32_dpp v198, v150 row_shr:2 row_mask:0xf bank_mask:0xf
	v_mov_b32_dpp v195, v151 row_shr:1 row_mask:0xf bank_mask:0xf
	v_mov_b32_dpp v199, v151 row_shr:2 row_mask:0xf bank_mask:0xf
	v_mov_b32_dpp v196, v152 row_shr:1 row_mask:0xf bank_mask:0xf
	v_mov_b32_dpp v200, v152 row_shr:2 row_mask:0xf bank_mask:0xf
	v_mov_b32_dpp v197, v153 row_shr:1 row_mask:0xf bank_mask:0xf
	v_mov_b32_dpp v201, v153 row_shr:2 row_mask:0xf bank_mask:0xf
	v_mul_f32_e32 v190, v138, v198
	v_mul_f32_e32 v191, v139, v199
	v_mul_f32_e32 v192, v140, v200
	v_mul_f32_e32 v193, v141, v201
	v_fmac_f32_e32 v190, v142, v194
	v_fmac_f32_e32 v191, v143, v195
	v_fmac_f32_e32 v192, v144, v196
	v_fmac_f32_e32 v193, v145, v197
	v_fmac_f32_e32 v190, v146, v150
	v_fmac_f32_e32 v191, v147, v151
	v_fmac_f32_e32 v192, v148, v152
	v_fmac_f32_e32 v193, v149, v153
	v_mul_f32_e32 v190, v158, v190
	v_mul_f32_e32 v191, v159, v191
	v_mul_f32_e32 v192, v160, v192
	v_mul_f32_e32 v193, v161, v193
	v_cvt_pk_bf16_f32 v230, v190, v191
	v_cvt_pk_bf16_f32 v231, v192, v193
	global_store_dwordx2 v[204:205], v[230:231], off
	v_add_co_u32_e32 v204, vcc, 0x22000, v204
	s_nop 1
	v_addc_co_u32_e32 v205, vcc, 0, v205, vcc
	v_fmamk_f32 v202, v131, 0x3a800000, v209
	v_rsq_f32_e32 v202, v202
	v_mul_f32_e32 v154, v20, v12
	v_mul_f32_e32 v155, v21, v13
	v_mul_f32_e32 v156, v22, v14
	v_mul_f32_e32 v157, v23, v15
	v_mul_f32_e32 v203, v202, v202
	v_mul_f32_e32 v154, v154, v203
	v_mul_f32_e32 v155, v155, v203
	v_mul_f32_e32 v156, v156, v203
	v_mul_f32_e32 v157, v157, v203
	v_mul_f32_e32 v158, v0, v202
	v_mul_f32_e32 v159, v1, v202
	v_mul_f32_e32 v160, v2, v202
	v_mul_f32_e32 v161, v3, v202
	v_min_f32_e64 v162, -v158, s52
	v_min_f32_e64 v163, -v159, s52
	v_min_f32_e64 v164, -v160, s52
	v_min_f32_e64 v165, -v161, s52
	v_mul_f32_e32 v162, 0x3fb8aa3b, v162
	v_mul_f32_e32 v163, 0x3fb8aa3b, v163
	v_mul_f32_e32 v164, 0x3fb8aa3b, v164
	v_mul_f32_e32 v165, 0x3fb8aa3b, v165
	v_exp_f32_e32 v162, v162
	v_exp_f32_e32 v163, v163
	v_exp_f32_e32 v164, v164
	v_exp_f32_e32 v165, v165
	s_nop 0
	v_add_f32_e32 v162, 1.0, v162
	v_add_f32_e32 v163, 1.0, v163
	v_add_f32_e32 v164, 1.0, v164
	v_add_f32_e32 v165, 1.0, v165
	v_mul_f32_e32 v166, v162, v163
	v_mul_f32_e32 v167, v164, v165
	v_rcp_f32_e32 v166, v166
	v_rcp_f32_e32 v167, v167
	s_nop 0
	v_mul_f32_e32 v206, v163, v166
	v_mul_f32_e32 v163, v162, v166
	v_mov_b32_e32 v162, v206
	v_mul_f32_e32 v206, v165, v167
	v_mul_f32_e32 v165, v164, v167
	v_mov_b32_e32 v164, v206
	v_mul_f32_e32 v158, v158, v162
	v_mul_f32_e32 v159, v159, v163
	v_mul_f32_e32 v160, v160, v164
	v_mul_f32_e32 v161, v161, v165
	v_mul_f32_e32 v162, v4, v202
	v_mul_f32_e32 v163, v5, v202
	v_mul_f32_e32 v164, v6, v202
	v_mul_f32_e32 v165, v7, v202
	v_mul_f32_e32 v158, v162, v158
	v_mul_f32_e32 v159, v163, v159
	v_mul_f32_e32 v160, v164, v160
	v_mul_f32_e32 v161, v165, v161
	v_mov_b32_dpp v194, v150 row_ror:1 row_mask:0xf bank_mask:0xf
	v_mov_b32_dpp v198, v150 row_ror:2 row_mask:0xf bank_mask:0xf
	v_mov_b32_dpp v195, v151 row_ror:1 row_mask:0xf bank_mask:0xf
	v_mov_b32_dpp v199, v151 row_ror:2 row_mask:0xf bank_mask:0xf
	v_mov_b32_dpp v196, v152 row_ror:1 row_mask:0xf bank_mask:0xf
	v_mov_b32_dpp v200, v152 row_ror:2 row_mask:0xf bank_mask:0xf
	v_mov_b32_dpp v197, v153 row_ror:1 row_mask:0xf bank_mask:0xf
	v_mov_b32_dpp v201, v153 row_ror:2 row_mask:0xf bank_mask:0xf
	s_nop 1
	v_mov_b32_dpp v194, v154 row_shr:1 row_mask:0xf bank_mask:0xf
	v_mov_b32_dpp v198, v154 row_shr:2 row_mask:0xf bank_mask:0xf
	v_mov_b32_dpp v195, v155 row_shr:1 row_mask:0xf bank_mask:0xf
	v_mov_b32_dpp v199, v155 row_shr:2 row_mask:0xf bank_mask:0xf
	v_mov_b32_dpp v196, v156 row_shr:1 row_mask:0xf bank_mask:0xf
	v_mov_b32_dpp v200, v156 row_shr:2 row_mask:0xf bank_mask:0xf
	v_mov_b32_dpp v197, v157 row_shr:1 row_mask:0xf bank_mask:0xf
	v_mov_b32_dpp v201, v157 row_shr:2 row_mask:0xf bank_mask:0xf
	v_mul_f32_e32 v190, v138, v198
	v_mul_f32_e32 v191, v139, v199
	v_mul_f32_e32 v192, v140, v200
	v_mul_f32_e32 v193, v141, v201
	v_fmac_f32_e32 v190, v142, v194
	v_fmac_f32_e32 v191, v143, v195
	v_fmac_f32_e32 v192, v144, v196
	v_fmac_f32_e32 v193, v145, v197
	v_fmac_f32_e32 v190, v146, v154
	v_fmac_f32_e32 v191, v147, v155
	v_fmac_f32_e32 v192, v148, v156
	v_fmac_f32_e32 v193, v149, v157
	v_mul_f32_e32 v190, v158, v190
	v_mul_f32_e32 v191, v159, v191
	v_mul_f32_e32 v192, v160, v192
	v_mul_f32_e32 v193, v161, v193
	v_cvt_pk_bf16_f32 v230, v190, v191
	v_cvt_pk_bf16_f32 v231, v192, v193
	global_store_dwordx2 v[204:205], v[230:231], off
	v_cvt_pk_bf16_f32 v232, v154, v155
	v_cvt_pk_bf16_f32 v233, v156, v157
	s_mov_b64 exec, s[72:73]
	global_store_dwordx2 v[204:205], v[232:233], off offset:2048
	s_mov_b64 exec, -1
	s_branch .LBB0_351

; __device__ void phase_prologue(KP P, LAS unsigned char* lds) {
;     ...
;         if (job < 3328) { const int l = job / 1664, r = job % 1664, jt = r >> 4, kt = r & 15, j0 = jt * 64; int src, valid = 64;
;             if (j0 < 1280) src = j0;
;             else if (j0 < 2304) src = 1296 + (j0 - 1280);
;             else if (j0 < 4352) { const int i = (j0 - 2304) >> 8, w = (j0 - 2304) & 255; src = (w < 128) ? 3344 + 128 * i + w : 5392 + 128 * i + (w - 128); }
;             else if (j0 < 6400) { const int i = (j0 - 4352) >> 8, w = (j0 - 4352) & 255; src = (w < 128) ? 2320 + 128 * i + w : 4368 + 128 * i + (w - 128); }
;             else if (j0 == 6400) { src = 1280; valid = 16; }
;             else { src = 0; valid = 0; }
;             transpose_tile_wave(P->w_in + (size_t)l * 1024 * 6416, 6416, kt * 64, src, valid, P->norm_pre + l * 1024, (bf16_t*)(ws + OFF_BTIN) + (size_t)l * NIN * 1024, 1024, j0, lane);
.LBB0_395:
	s_or_b64 exec, exec, s[18:19]
	v_add_u32_e32 v2, 0xfffff700, v75
	v_lshrrev_b32_e32 v3, 6, v2
	v_and_b32_e32 v3, 3, v3
	v_lshrrev_b32_e32 v10, 2, v8
	v_and_b32_e32 v10, 1, v10
	v_and_or_b32 v10, v3, 2, v10
	v_lshlrev_b32_e32 v11, 1, v10
	v_and_b32_e32 v11, 2, v11
	v_lshrrev_b32_e32 v10, 1, v10
	v_or_b32_e32 v10, v11, v10
	v_lshlrev_b32_e32 v10, 10, v10
	v_lshrrev_b32_e32 v11, 8, v2
	v_lshl_add_u32 v10, v11, 6, v10
	v_and_b32_e32 v3, 1, v3
	v_lshl_add_u32 v10, v3, 5, v10
	v_lshrrev_b32_e32 v11, 5, v8
	v_lshl_add_u32 v10, v11, 4, v10
	v_lshrrev_b32_e32 v11, 3, v8
	v_and_b32_e32 v11, 3, v11
	v_lshl_add_u32 v10, v11, 2, v10
	v_and_b32_e32 v11, 3, v8
	v_add_u32_e32 v10, 0x910, v10
	v_add_u32_e32 v10, v10, v11
	v_sub_u32_e32 v10, v10, v8
	s_movk_i32 s24, 0x1000
	v_cmp_gt_u32_e32 vcc, s24, v2
	s_nop 1
	v_cndmask_b32_e32 v0, v0, v10, vcc
	s_load_dwordx2 s[24:25], s[36:37], 0x20
	s_load_dwordx2 s[18:19], s[36:37], 0x10
	v_lshlrev_b32_e32 v1, 6, v1
	v_sub_u32_e32 v1, v7, v1
	v_and_b32_e32 v76, 0x3c0, v1
	s_waitcnt lgkmcnt(0)
	v_mov_b64_e32 v[2:3], s[24:25]
	s_mov_b32 s24, 0x1910000
	v_mul_u32_u24_e32 v1, 0x1910, v76
	v_mad_i64_i32 v[2:3], s[24:25], v74, s24, v[2:3]
	v_lshlrev_b32_e32 v168, 2, v1
	v_lshl_add_u64 v[2:3], v[2:3], 0, v[168:169]
	v_ashrrev_i32_e32 v1, 31, v0
	v_lshl_add_u64 v[0:1], v[0:1], 2, v[2:3]
	v_lshlrev_b32_e32 v168, 2, v8
	v_lshl_add_u64 v[40:41], v[0:1], 0, v[168:169]
	v_mov_b32_e32 v1, 0
	v_mov_b32_e32 v0, 0
	s_and_saveexec_b64 s[24:25], s[22:23]
	s_cbranch_execz .LBB0_397
	global_load_dword v0, v[40:41], off nt
